# GEMM unit end: leading half's alignment barrier moved two store groups into its epilogue
# speedup vs baseline: 1.0129x; 1.0129x over previous
.Lk_done:
	s_add_u32 s52, s0, 0x80
	s_addc_u32 s53, s1, 0
	v_lshl_add_u64 v[144:145], s[52:53], 0, v[136:137]
	s_add_i32 m0, s9, 0xc000
	global_load_lds_dwordx4 v[144:145], off
	v_lshl_add_u64 v[144:145], s[52:53], 0, v[138:139]
	s_add_i32 m0, s9, 0xe000
	s_nop 0
	global_load_lds_dwordx4 v[144:145], off
	v_readlane_b32 s42, v233, 50
	v_readlane_b32 s43, v233, 51
	s_and_b64 vcc, exec, s[42:43]
	s_cselect_b32 s101, 1, 0

.LBB0_351:
	s_cmp_eq_u32 s101, 0
	s_cbranch_scc1 .Lal_p0
	s_barrier
	s_mov_b32 s101, 0

.LBB0_375:
.LBB0_376:
	s_cmp_eq_u32 s101, 0
	s_cbranch_scc1 .Lal_fb
	s_barrier
	s_mov_b32 s101, 0
